# fin GN/token-shift loop: Y0,Y1,V,N0,N1,COEF loads issued together per iteration (masked neighbour loads), single wait
# speedup vs baseline: 1.0395x; 1.0017x over previous
.LBB0_362:
	v_add_u32_e32 v32, s2, v57
	v_ashrrev_i32_e32 v44, 4, v32
	v_ashrrev_i32_e32 v45, 31, v44
	v_lshl_add_u64 v[46:47], v[44:45], 0, s[96:97]
	s_mov_b64 s[16:17], 0x1fff
	v_cmp_lt_u64_e32 vcc, s[16:17], v[46:47]
	v_mov_b32_e32 v32, 0xff
	v_mov_b32_e32 v33, 0x7ff
	v_cndmask_b32_e32 v45, v32, v33, vcc
	v_lshlrev_b64 v[32:33], 10, v[46:47]
	v_lshl_add_u64 v[34:35], v[38:39], 0, v[32:33]
	v_lshl_add_u64 v[32:33], v[40:41], 0, v[32:33]
	global_load_dwordx4 v[48:51], v[34:35], off
	global_load_dwordx4 v[52:55], v[32:33], off
	v_mov_b64_e32 v[32:33], s[40:41]
	v_mad_u64_u32 v[32:33], s[16:17], v46, s43, v[32:33]
	v_mad_i32_i24 v33, v47, s43, v33
	v_lshl_add_u64 v[64:65], v[36:37], 1, v[32:33]
	global_load_dwordx4 v[32:35], v[64:65], off offset:2048
	v_and_b32_e32 v63, v45, v46
	v_mov_b32_e32 v62, 0
	v_cmp_ne_u32_e32 vcc, 0, v63
	v_mov_b32_e32 v104, 0
	v_mov_b32_e32 v105, 0
	v_mov_b32_e32 v106, 0
	v_mov_b32_e32 v107, 0
	s_and_saveexec_b64 s[16:17], vcc
	global_load_dwordx4 v[104:107], v[64:65], off offset:-1024
	s_or_b64 exec, exec, s[16:17]
	s_mov_b64 s[16:17], 0x1000
	v_lshl_add_u64 v[114:115], v[64:65], 0, s[16:17]
	v_cmp_ne_u32_e32 vcc, v63, v45
	v_mov_b32_e32 v108, 0
	v_mov_b32_e32 v109, 0
	v_mov_b32_e32 v110, 0
	v_mov_b32_e32 v111, 0
	s_and_saveexec_b64 s[16:17], vcc
	global_load_dwordx4 v[108:111], v[114:115], off offset:1024
	s_or_b64 exec, exec, s[16:17]
	v_lshlrev_b64 v[116:117], 6, v[46:47]
	v_lshl_add_u64 v[116:117], v[42:43], 0, v[116:117]
	global_load_dwordx2 v[112:113], v[116:117], off
	s_waitcnt vmcnt(0)
	v_and_b32_e32 v67, 0xffff0000, v51
	v_lshlrev_b32_e32 v66, 16, v51
	v_and_b32_e32 v69, 0xffff0000, v55
	v_lshlrev_b32_e32 v68, 16, v55
	v_and_b32_e32 v51, 0xffff0000, v50
	v_lshlrev_b32_e32 v50, 16, v50
	v_and_b32_e32 v55, 0xffff0000, v54
	v_lshlrev_b32_e32 v54, 16, v54
	v_pk_add_f32 v[66:67], v[66:67], v[68:69]
	v_pk_add_f32 v[54:55], v[50:51], v[54:55]
	v_and_b32_e32 v51, 0xffff0000, v49
	v_lshlrev_b32_e32 v50, 16, v49
	v_and_b32_e32 v69, 0xffff0000, v53
	v_lshlrev_b32_e32 v68, 16, v53
	v_and_b32_e32 v49, 0xffff0000, v48
	v_lshlrev_b32_e32 v48, 16, v48
	v_and_b32_e32 v53, 0xffff0000, v52
	v_lshlrev_b32_e32 v52, 16, v52
	v_pk_add_f32 v[48:49], v[48:49], v[52:53]
	v_pk_add_f32 v[50:51], v[50:51], v[68:69]
	v_add_f32_e32 v52, 0, v48
	v_add_f32_e32 v52, v49, v52
	v_add_f32_e32 v52, v50, v52
	v_add_f32_e32 v52, v51, v52
	v_add_f32_e32 v52, v54, v52
	v_add_f32_e32 v52, v55, v52
	v_add_f32_e32 v52, v66, v52
	v_add_f32_e32 v52, v67, v52
	s_nop 1
	v_add_f32_dpp v52, v52, v52 quad_perm:[1,0,3,2] row_mask:0xf bank_mask:0xf bound_ctrl:1
	s_nop 1
	v_add_f32_dpp v52, v52, v52 quad_perm:[2,3,0,1] row_mask:0xf bank_mask:0xf bound_ctrl:1
	s_nop 1
	v_add_f32_dpp v52, v52, v52 row_half_mirror row_mask:0xf bank_mask:0xf bound_ctrl:1
	v_mul_f32_e32 v68, 0x3c800000, v52
	v_pk_add_f32 v[48:49], v[48:49], v[68:69] op_sel_hi:[1,0] neg_lo:[0,1] neg_hi:[0,1]
	v_pk_add_f32 v[50:51], v[50:51], v[68:69] op_sel_hi:[1,0] neg_lo:[0,1] neg_hi:[0,1]
	v_pk_mul_f32 v[70:71], v[48:49], v[48:49]
	v_pk_mul_f32 v[72:73], v[50:51], v[50:51]
	v_pk_add_f32 v[52:53], v[54:55], v[68:69] op_sel_hi:[1,0] neg_lo:[0,1] neg_hi:[0,1]
	v_pk_add_f32 v[54:55], v[66:67], v[68:69] op_sel_hi:[1,0] neg_lo:[0,1] neg_hi:[0,1]
	v_add_f32_e32 v68, v70, v71
	v_add_f32_e32 v68, v72, v68
	v_pk_mul_f32 v[74:75], v[52:53], v[52:53]
	v_add_f32_e32 v68, v73, v68
	v_add_f32_e32 v68, v74, v68
	v_pk_mul_f32 v[66:67], v[54:55], v[54:55]
	v_add_f32_e32 v68, v75, v68
	v_add_f32_e32 v66, v66, v68
	v_add_f32_e32 v66, v67, v66
	v_mov_b32_e32 v67, 0
	v_mov_b32_e32 v68, 0
	v_add_f32_dpp v66, v66, v66 quad_perm:[1,0,3,2] row_mask:0xf bank_mask:0xf bound_ctrl:1
	v_mov_b32_e32 v69, 0
	v_mov_b32_e32 v70, 0
	v_add_f32_dpp v83, v66, v66 quad_perm:[2,3,0,1] row_mask:0xf bank_mask:0xf bound_ctrl:1
	v_mov_b32_e32 v66, 0
	v_mov_b32_e32 v71, 0
	v_mov_b32_dpp v84, v83 row_half_mirror row_mask:0xf bank_mask:0xf bound_ctrl:1
	v_mov_b32_e32 v72, 0
	v_mov_b32_e32 v73, 0
	v_and_b32_e32 v73, 0xffff0000, v104
	v_lshlrev_b32_e32 v72, 16, v104
	v_and_b32_e32 v71, 0xffff0000, v105
	v_lshlrev_b32_e32 v70, 16, v105
	v_and_b32_e32 v69, 0xffff0000, v106
	v_lshlrev_b32_e32 v68, 16, v106
	v_and_b32_e32 v67, 0xffff0000, v107
	v_lshlrev_b32_e32 v66, 16, v107
	v_mov_b32_e32 v63, 0
	v_mov_b32_e32 v74, 0
	v_mov_b32_e32 v75, 0
	v_mov_b32_e32 v76, 0
	v_mov_b32_e32 v77, 0
	v_mov_b32_e32 v78, 0
	v_mov_b32_e32 v79, 0
	v_and_b32_e32 v79, 0xffff0000, v108
	v_lshlrev_b32_e32 v78, 16, v108
	v_and_b32_e32 v77, 0xffff0000, v109
	v_lshlrev_b32_e32 v76, 16, v109
	v_and_b32_e32 v75, 0xffff0000, v110
	v_lshlrev_b32_e32 v74, 16, v110
	v_and_b32_e32 v63, 0xffff0000, v111
	v_lshlrev_b32_e32 v62, 16, v111
	v_and_b32_e32 v65, 0xffff0000, v34
	v_lshlrev_b32_e32 v64, 16, v34
	v_add_f32_e32 v34, v83, v84
	v_and_b32_e32 v85, 0xffff0000, v35
	v_lshlrev_b32_e32 v84, 16, v35
	v_mad_u64_u32 v[44:45], s[16:17], v44, s42, v[56:57]
	v_mov_b32_e32 v35, 0x3a27c5ac
	v_and_b32_e32 v87, 0xffff0000, v33
	v_lshlrev_b32_e32 v86, 16, v33
	v_and_b32_e32 v33, 0xffff0000, v32
	v_lshlrev_b32_e32 v32, 16, v32
	v_fmamk_f32 v45, v34, 0x3c800000, v35
	v_pk_add_f32 v[34:35], v[72:73], v[32:33] neg_lo:[0,1] neg_hi:[0,1]
	v_pk_add_f32 v[72:73], v[78:79], v[32:33] neg_lo:[0,1] neg_hi:[0,1]
	v_mul_f32_e32 v78, 0x4b800000, v45
	v_cmp_gt_f32_e32 vcc, s57, v45
	v_pk_add_f32 v[68:69], v[68:69], v[64:65] neg_lo:[0,1] neg_hi:[0,1]
	v_pk_add_f32 v[74:75], v[74:75], v[64:65] neg_lo:[0,1] neg_hi:[0,1]
	v_cndmask_b32_e32 v45, v45, v78, vcc
	v_rsq_f32_e32 v45, v45
	v_pk_fma_f32 v[68:69], v[0:1], v[68:69], v[64:65]
	v_pk_fma_f32 v[64:65], v[8:9], v[74:75], v[64:65]
	v_pk_add_f32 v[70:71], v[70:71], v[86:87] neg_lo:[0,1] neg_hi:[0,1]
	v_mul_f32_e32 v74, 0x45800000, v45
	v_cndmask_b32_e32 v74, v45, v74, vcc
	v_pk_add_f32 v[66:67], v[66:67], v[84:85] neg_lo:[0,1] neg_hi:[0,1]
	v_pk_mul_f32 v[48:49], v[48:49], v[74:75] op_sel_hi:[1,0]
	v_pk_mul_f32 v[50:51], v[50:51], v[74:75] op_sel_hi:[1,0]
	v_pk_mul_f32 v[52:53], v[52:53], v[74:75] op_sel_hi:[1,0]
	v_pk_mul_f32 v[54:55], v[54:55], v[74:75] op_sel_hi:[1,0]
	v_pk_add_f32 v[76:77], v[76:77], v[86:87] neg_lo:[0,1] neg_hi:[0,1]
	v_pk_add_f32 v[62:63], v[62:63], v[84:85] neg_lo:[0,1] neg_hi:[0,1]
	v_pk_fma_f32 v[34:35], v[4:5], v[34:35], v[32:33]
	v_pk_fma_f32 v[70:71], v[6:7], v[70:71], v[86:87]
	v_pk_fma_f32 v[66:67], v[2:3], v[66:67], v[84:85]
	v_pk_fma_f32 v[48:49], v[20:21], v[48:49], v[28:29]
	v_pk_fma_f32 v[50:51], v[22:23], v[50:51], v[30:31]
	v_pk_fma_f32 v[52:53], v[16:17], v[52:53], v[24:25]
	v_pk_fma_f32 v[54:55], v[18:19], v[54:55], v[26:27]
	v_pk_fma_f32 v[32:33], v[12:13], v[72:73], v[32:33]
	v_pk_fma_f32 v[72:73], v[14:15], v[76:77], v[86:87]
	v_pk_fma_f32 v[62:63], v[10:11], v[62:63], v[84:85]
	s_addk_i32 s2, 0x100
	s_cmpk_eq_i32 s2, 0x400
	v_pk_fma_f32 v[34:35], v[34:35], v[112:113], v[48:49] op_sel_hi:[1, 0, 1]
	v_pk_fma_f32 v[48:49], v[70:71], v[112:113], v[50:51] op_sel_hi:[1, 0, 1]
	v_pk_fma_f32 v[50:51], v[68:69], v[112:113], v[52:53] op_sel_hi:[1, 0, 1]
	v_pk_fma_f32 v[52:53], v[66:67], v[112:113], v[54:55] op_sel_hi:[1, 0, 1]
	v_pk_fma_f32 v[32:33], v[112:113], v[32:33], v[34:35] op_sel:[1, 0, 0]
	v_pk_fma_f32 v[34:35], v[72:73], v[112:113], v[48:49] op_sel:[0, 1, 0]
	v_pk_fma_f32 v[48:49], v[64:65], v[112:113], v[50:51] op_sel:[0, 1, 0]
	v_pk_fma_f32 v[46:47], v[62:63], v[112:113], v[52:53] op_sel:[0, 1, 0]
	v_cvt_pk_bf16_f32 v32, v32, v33
	v_cvt_pk_bf16_f32 v33, v34, v35
	v_cvt_pk_bf16_f32 v34, v48, v49
	v_cvt_pk_bf16_f32 v35, v46, v47
	ds_write_b128 v44, v[32:35] offset:36864
	s_cbranch_scc1 .LBB0_366
	s_branch .LBB0_362
